# P1 silu-tile epilogue re-issued four elements at a time with packed f32 multiplies/adds (p1skip wave flag moved to s32); on top of p8pk + czero
# speedup vs baseline: 1.0130x; 1.0069x over previous
;     __device__ bool next(int i, Unit& u) const { if (!so.next(i >> 1, u)) return false; u.sel = i & 1; return true; }
;     __host__ __device__ bool next(int i, Unit& u) const {
;         const long L = (long)i * G + c; if (L >= nwg) return false;
;         int wgid = (int)L; { const int q = nwg / NXCD, r = nwg % NXCD, xcd = wgid % NXCD, off = wgid / NXCD; wgid = (xcd < r ? xcd * (q + 1) : r * (q + 1) + (xcd - r) * q) + off; }
;         const int nig = WGM * nN, gid = wgid / nig, fm = gid * WGM, gsz = (nM - fm) < WGM ? (nM - fm) : WGM;
;         u.pm = fm + ((wgid % nig) % gsz); u.pn = (wgid % nig) / gsz; u.sel = 0; return true;
; template <class Epi, class Sched, bool ALIGN_EPI = false, bool SP2 = false>
; __device__ __forceinline__ void gemm_phase(PG8_LAS unsigned char* lds, const Gemm g, const Sched& S, const Epi& E) {
;     int tid_ = threadIdx.x; asm volatile("" : "+v"(tid_));
;     const int tid = tid_, wid = __builtin_amdgcn_readfirstlane(tid >> 6), lane = tid & 63, wr = wid >> 2, wc = wid & 3, fr = lane & 15, fq = lane >> 4;
.LBB0_192:
	s_or_b64 exec, exec, s[0:1]
	v_readfirstlane_b32 s32, v201
	s_nop 3
	s_bfe_u32 s32, s32, 0x20006
	s_cmp_lg_u32 s32, 0
	s_cselect_b32 s32, 3, 0
	v_mov_b32_e32 v1, v201
	s_cmpk_lt_i32 s2, 0x1b1b
	s_waitcnt lgkmcnt(0)
	s_barrier
	s_movk_i32 s0, 0x400
	v_readfirstlane_b32 s3, v1
	s_cselect_b64 s[4:5], -1, 0
	s_cmpk_gt_i32 s2, 0x1b1a
	s_cbranch_scc1 .LBB0_198
	s_ashr_i32 s1, s2, 31
	s_lshr_b32 s1, s1, 29
	s_add_i32 s1, s2, s1
	s_and_b32 s6, s1, -8
	s_sub_i32 s8, s2, s6
	s_cmp_gt_i32 s8, 2
	s_cbranch_scc0 .LBB0_195
	s_mul_i32 s6, s8, 0x363
	s_add_i32 s9, s6, 3
	s_cbranch_execz .LBB0_196
	s_branch .LBB0_197

; #define PG8_STAGE(bufoff, gbase, voff) do { _Pragma("unroll") for (int _i = 0; _i < 2; ++_i) \
;         __builtin_amdgcn_global_load_lds((const unsigned*)((const char*)(gbase) + (voff)[_i]), (PG8_LAS unsigned*)(lds + (bufoff) + ldsw + _i * 8192), 16, 0, 0); } while (0)
; #define PG8_LDA(dst, b, h) do { _Pragma("unroll") for (int m = 0; m < 4; ++m) _Pragma("unroll") for (int k = 0; k < 2; ++k) dst[m][k] = *(const PG8_LAS bf16x8*)(lds + PG8_SA(b, h) + aoff + m * 2048 + k * 1024); } while (0)
; #define PG8_LDB(dst, b, h) do { _Pragma("unroll") for (int n = 0; n < 2; ++n) _Pragma("unroll") for (int k = 0; k < 2; ++k) dst[n][k] = *(const PG8_LAS bf16x8*)(lds + PG8_SB(b, h) + boff + n * 2048 + k * 1024); } while (0)
; #define PG8_MMA(ai, bj, At, Bt) do { __builtin_amdgcn_s_setprio(1); _Pragma("unroll") for (int m = 0; m < 4; ++m) _Pragma("unroll") for (int n = 0; n < 2; ++n) _Pragma("unroll") for (int k = 0; k < 2; ++k) \
;         acc[ai][bj][m][n] = __builtin_amdgcn_mfma_f32_16x16x32_bf16(Bt[n][k], At[m][k], acc[ai][bj][m][n], 0, 0, 0); __builtin_amdgcn_s_setprio(0); } while (0)
; #define PG8_WAIT_V(n) asm volatile("s_waitcnt vmcnt(" #n ")" ::: "memory")
; #define PG8_WAIT_L(n) asm volatile("s_waitcnt lgkmcnt(" #n ")" ::: "memory")
; #define PG8_BAR __builtin_amdgcn_s_barrier()
; #define PG8_SCHED __builtin_amdgcn_sched_barrier(0)
; template <class Epi, class Sched, bool ALIGN_EPI = false, bool SP2 = false>
; __device__ __forceinline__ void gemm_phase(PG8_LAS unsigned char* lds, const Gemm g, const Sched& S, const Epi& E) {
;     ...
;         for (int t = 0; t < nt; t += 2) {
;             const bool last = (t == nt - 2);
;             const char* a1 = cA + (size_t)(t + 1) * kstep;
;             const char* a2 = last ? nA : cA + (size_t)(t + 2) * kstep; const char* b2 = last ? nB : cB + (size_t)(t + 2) * kstep;
;             const char* a3 = a2 + kstep; const char* b3 = b2 + kstep;
;             if (last && has_next) S.a_ready(nxt);
;             if constexpr (SP2) {
;             PG8_LDB(B0, 0, 0); PG8_LDB(B1, 0, 1); PG8_SCHED; PG8_LDA(At, 0, 0); PG8_STAGE(PG8_SA(1, 1), a1 + hstep, voffA);
;             PG8_WAIT_V(8); PG8_WAIT_L(0); PG8_BAR; PG8_MMA(0, 0, At, B0); PG8_MMA(0, 1, At, B1); PG8_BAR; PG8_SCHED;
.Lcz_go_216:
	v_mov_b32_e32 v1, 0
	s_cmp_eq_u32 s48, 0x100
	s_cselect_b32 s100, 1, 0
	s_cmp_eq_u32 s49, 26
	s_cselect_b32 s101, s32, 0
	s_or_b32 s100, s100, s101
	s_add_u32 s0, s72, 0x80
	s_addc_u32 s1, s73, 0
	s_add_u32 s61, s6, 0x100
	s_addc_u32 s72, s7, 0
	s_mov_b32 s6, 0
	ds_read_b128 v[130:133], v178
	ds_read_b128 v[134:137], v178 offset:1024
	ds_read_b128 v[138:141], v178 offset:2048
	ds_read_b128 v[142:145], v178 offset:3072
	ds_read_b128 v[168:171], v179
	ds_read_b128 v[172:175], v179 offset:1024
	ds_read_b128 v[182:185], v179 offset:2048
	ds_read_b128 v[186:189], v179 offset:3072
	s_add_i32 s73, s6, 2
	s_add_u32 vcc_lo, s0, 0x80
	s_addc_u32 s7, s1, 0
	s_cmp_eq_u32 s92, s6
	s_cselect_b32 s6, s62, vcc_lo
	s_cselect_b32 s7, s63, s7
	s_cselect_b32 vcc_hi, s71, s72
	s_cselect_b32 vcc_lo, s70, s61
	v_lshl_add_u64 v[198:199], s[0:1], 0, v[160:161]
	s_add_i32 m0, s77, 0xc000
	ds_read_b128 v[190:193], v180
	ds_read_b128 v[194:197], v180 offset:1024
	ds_read_b128 v[202:205], v180 offset:2048
	ds_read_b128 v[206:209], v180 offset:3072
	ds_read_b128 v[210:213], v180 offset:4096
	ds_read_b128 v[214:217], v180 offset:5120
	ds_read_b128 v[218:221], v180 offset:6144
	ds_read_b128 v[222:225], v180 offset:7168
	global_load_lds_dwordx4 v[198:199], off
	v_lshl_add_u64 v[198:199], s[0:1], 0, v[162:163]
	s_add_i32 m0, s77, 0xe000
	s_nop 0
	global_load_lds_dwordx4 v[198:199], off
	s_waitcnt vmcnt(8)
	s_waitcnt lgkmcnt(0)
	s_barrier
	s_setprio 1
	s_waitcnt lgkmcnt(0)
	s_bitcmp1_b32 s100, 1
	s_cbranch_scc1 .Lcz_z0_216
	v_mfma_f32_16x16x32_bf16 v[126:129], v[130:133], v[190:193], 0
	v_mfma_f32_16x16x32_bf16 v[122:125], v[138:141], v[190:193], 0
	v_mfma_f32_16x16x32_bf16 v[110:113], v[130:133], v[202:205], 0
	v_mfma_f32_16x16x32_bf16 v[106:109], v[138:141], v[202:205], 0
	v_mfma_f32_16x16x32_bf16 v[94:97], v[130:133], v[210:213], 0
	v_mfma_f32_16x16x32_bf16 v[90:93], v[138:141], v[210:213], 0
	v_mfma_f32_16x16x32_bf16 v[78:81], v[130:133], v[218:221], 0
	v_mfma_f32_16x16x32_bf16 v[74:77], v[138:141], v[218:221], 0
	v_mfma_f32_16x16x32_bf16 v[126:129], v[134:137], v[194:197], v[126:129]
	v_mfma_f32_16x16x32_bf16 v[122:125], v[142:145], v[194:197], v[122:125]
	v_mfma_f32_16x16x32_bf16 v[110:113], v[134:137], v[206:209], v[110:113]
	v_mfma_f32_16x16x32_bf16 v[106:109], v[142:145], v[206:209], v[106:109]
	v_mfma_f32_16x16x32_bf16 v[94:97], v[134:137], v[214:217], v[94:97]
	v_mfma_f32_16x16x32_bf16 v[90:93], v[142:145], v[214:217], v[90:93]
	v_mfma_f32_16x16x32_bf16 v[78:81], v[134:137], v[222:225], v[78:81]
	v_mfma_f32_16x16x32_bf16 v[74:77], v[142:145], v[222:225], v[74:77]
	s_setprio 0
	s_setprio 1
	v_mfma_f32_16x16x32_bf16 v[118:121], v[168:171], v[190:193], 0
	v_mfma_f32_16x16x32_bf16 v[114:117], v[182:185], v[190:193], 0
	v_mfma_f32_16x16x32_bf16 v[102:105], v[168:171], v[202:205], 0
	v_mfma_f32_16x16x32_bf16 v[98:101], v[182:185], v[202:205], 0
	v_mfma_f32_16x16x32_bf16 v[86:89], v[168:171], v[210:213], 0
	v_mfma_f32_16x16x32_bf16 v[82:85], v[182:185], v[210:213], 0
	v_mfma_f32_16x16x32_bf16 v[70:73], v[168:171], v[218:221], 0
	v_mfma_f32_16x16x32_bf16 v[66:69], v[182:185], v[218:221], 0
	v_mfma_f32_16x16x32_bf16 v[118:121], v[172:175], v[194:197], v[118:121]
	v_mfma_f32_16x16x32_bf16 v[114:117], v[186:189], v[194:197], v[114:117]
	v_mfma_f32_16x16x32_bf16 v[102:105], v[172:175], v[206:209], v[102:105]
	v_mfma_f32_16x16x32_bf16 v[98:101], v[186:189], v[206:209], v[98:101]
	v_mfma_f32_16x16x32_bf16 v[86:89], v[172:175], v[214:217], v[86:89]
	v_mfma_f32_16x16x32_bf16 v[82:85], v[186:189], v[214:217], v[82:85]
	v_mfma_f32_16x16x32_bf16 v[70:73], v[172:175], v[222:225], v[70:73]
	v_mfma_f32_16x16x32_bf16 v[66:69], v[186:189], v[222:225], v[66:69]

; __device__ __forceinline__ u32x4 pack8(const f32x4 a, const f32x4 b) { u32x4 w; w.x = cvt_pk_bf16(a[0], a[1]); w.y = cvt_pk_bf16(a[2], a[3]); w.z = cvt_pk_bf16(b[0], b[1]); w.w = cvt_pk_bf16(b[2], b[3]); return w; }
; #define EPI_ROWLOOP _Pragma("unroll") for (int ai = 0; ai < 2; ++ai) _Pragma("unroll") for (int m = 0; m < 4; ++m)
; __device__ __forceinline__ float sigm(float x) { return __builtin_amdgcn_rcpf(1.0f + __builtin_amdgcn_exp2f(x * -1.4426950408889634f)); }
; __device__ __forceinline__ float sigm_new(float x) { return __builtin_amdgcn_rcpf(1.0f + __builtin_amdgcn_exp2f(x * -1.4426950408889634f)); }
; __device__ __forceinline__ f32x4 sigm4_new(const f32x4 v) { f32x4 o; o[0] = sigm_new(v[0]); o[1] = sigm_new(v[1]); o[2] = sigm_new(v[2]); o[3] = sigm_new(v[3]); return o; }
; __device__ __forceinline__ f32x4 silu4_new(const f32x4 v) { return v * sigm4_new(v); }
; __device__ __forceinline__ f32x4 sigm4(const f32x4 v) { f32x4 o; o[0] = sigm(v[0]); o[1] = sigm(v[1]); o[2] = sigm(v[2]); o[3] = sigm(v[3]); return o; }
; __device__ __forceinline__ f32x4 silu4(const f32x4 v) { return v * sigm4(v); }
;     __device__ __forceinline__ void operator()(const f32x4 (&acc)[2][2][4][2], const Unit& u, int wr, int wc, int fr, int fq) const {
;     ...
;         if (pn < 16) {
;             bf16_t* base = pn < 4 ? HQ : pn < 8 ? HF : pn < 12 ? HI : HG; const bool act = (pn < 4) || (pn >= 12);
;             const int col0 = (pn & 3) * 256 + cl;
;             EPI_ROWLOOP { bf16_t* rowp = base + (size_t)(row0 + ai * HALF + m * 16) * 1024 + col0;
; #pragma unroll
;                 for (int bj = 0; bj < 2; ++bj) { f32x4 v0 = acc[ai][bj][m][0], v1 = acc[ai][bj][m][1]; if (act) { v0 = silu4(v0); v1 = silu4(v1); }
;                     *(u32x4*)(rowp + bj * HALF) = pack8(v0, v1); } }
.LBB0_282:
	s_mov_b32 s100, 0xbfb8aa3b
	s_mov_b32 s101, 0xbfb8aa3b
	s_mov_b32 s98, 1.0
	s_mov_b32 s99, 1.0
	s_waitcnt lgkmcnt(0)
	v_sub_co_u32_e64 v1, s[6:7], s49, 12
	v_cmp_lt_u32_e32 vcc, -9, v1
	v_cmp_gt_u32_e64 s[0:1], -8, v1
	s_cbranch_vccnz .LBB0_284
	v_pk_mul_f32 v[130:131], v[126:127], s[100:101]
	v_pk_mul_f32 v[132:133], v[128:129], s[100:101]
	v_exp_f32_e32 v130, v130
	v_exp_f32_e32 v131, v131
	v_exp_f32_e32 v132, v132
	v_exp_f32_e32 v133, v133
	v_pk_add_f32 v[130:131], v[130:131], s[98:99]
	v_pk_add_f32 v[132:133], v[132:133], s[98:99]
	v_rcp_f32_e32 v130, v130
	v_rcp_f32_e32 v131, v131
	v_rcp_f32_e32 v132, v132
	v_rcp_f32_e32 v133, v133
	v_pk_mul_f32 v[126:127], v[126:127], v[130:131]
	v_pk_mul_f32 v[128:129], v[128:129], v[132:133]
	v_pk_mul_f32 v[130:131], v[122:123], s[100:101]
	v_pk_mul_f32 v[132:133], v[124:125], s[100:101]
	v_exp_f32_e32 v130, v130
	v_exp_f32_e32 v131, v131
	v_exp_f32_e32 v132, v132
	v_exp_f32_e32 v133, v133
	v_pk_add_f32 v[130:131], v[130:131], s[98:99]
	v_pk_add_f32 v[132:133], v[132:133], s[98:99]
	v_rcp_f32_e32 v130, v130
	v_rcp_f32_e32 v131, v131
	v_rcp_f32_e32 v132, v132
	v_rcp_f32_e32 v133, v133
	v_pk_mul_f32 v[122:123], v[122:123], v[130:131]
	v_pk_mul_f32 v[124:125], v[124:125], v[132:133]
.LBB0_284:
	s_and_b64 s[6:7], s[6:7], exec
	s_cselect_b32 s6, s39, s41
	s_cselect_b32 s7, s38, s40
	s_cmp_lt_u32 s49, 8
	s_cselect_b32 s16, s24, s7
	s_cselect_b32 s6, s25, s6
	s_cmp_lt_i32 s49, 4
	s_cselect_b32 s7, s35, s6
	s_cselect_b32 s6, s34, s16
	s_lshl_b32 s16, s49, 8
	s_and_b32 s16, s16, 0x300
	v_or_b32_e32 v1, s16, v154
	v_lshlrev_b32_e32 v130, 1, v1
	v_mov_b32_e32 v131, v0
	v_ashrrev_i32_e32 v169, 31, v168
	v_lshl_add_u64 v[130:131], s[6:7], 0, v[130:131]
	v_lshlrev_b64 v[132:133], 11, v[168:169]
	v_cndmask_b32_e64 v1, 0, 1, s[0:1]
	v_lshl_add_u64 v[132:133], v[130:131], 0, v[132:133]
	v_cvt_pk_bf16_f32 v126, v126, v127
	v_cvt_pk_bf16_f32 v127, v128, v129
	v_cvt_pk_bf16_f32 v128, v122, v123
	v_cvt_pk_bf16_f32 v129, v124, v125
	v_cmp_ne_u32_e64 s[6:7], 1, v1
	s_andn2_b64 vcc, exec, s[0:1]
	global_store_dwordx4 v[132:133], v[126:129], off
	s_cbranch_vccnz .LBB0_286
	v_pk_mul_f32 v[122:123], v[118:119], s[100:101]
	v_pk_mul_f32 v[124:125], v[120:121], s[100:101]
	v_exp_f32_e32 v122, v122
	v_exp_f32_e32 v123, v123
	v_exp_f32_e32 v124, v124
	v_exp_f32_e32 v125, v125
	v_pk_add_f32 v[122:123], v[122:123], s[98:99]
	v_pk_add_f32 v[124:125], v[124:125], s[98:99]
	v_rcp_f32_e32 v122, v122
	v_rcp_f32_e32 v123, v123
	v_rcp_f32_e32 v124, v124
	v_rcp_f32_e32 v125, v125
	v_pk_mul_f32 v[118:119], v[118:119], v[122:123]
	v_pk_mul_f32 v[120:121], v[120:121], v[124:125]
	v_pk_mul_f32 v[122:123], v[114:115], s[100:101]
	v_pk_mul_f32 v[124:125], v[116:117], s[100:101]
	v_exp_f32_e32 v122, v122
	v_exp_f32_e32 v123, v123
	v_exp_f32_e32 v124, v124
	v_exp_f32_e32 v125, v125
	v_pk_add_f32 v[122:123], v[122:123], s[98:99]
	v_pk_add_f32 v[124:125], v[124:125], s[98:99]
	v_rcp_f32_e32 v122, v122
	v_rcp_f32_e32 v123, v123
	v_rcp_f32_e32 v124, v124
	v_rcp_f32_e32 v125, v125
	v_pk_mul_f32 v[114:115], v[114:115], v[122:123]
	v_pk_mul_f32 v[116:117], v[116:117], v[124:125]
.LBB0_286:
	v_cvt_pk_bf16_f32 v118, v118, v119
	v_cvt_pk_bf16_f32 v119, v120, v121
	v_cvt_pk_bf16_f32 v120, v114, v115
	v_cvt_pk_bf16_f32 v121, v116, v117
	s_and_b64 vcc, exec, s[6:7]
	global_store_dwordx4 v[132:133], v[118:121], off offset:256
	s_cbranch_vccnz .LBB0_288
	v_pk_mul_f32 v[114:115], v[110:111], s[100:101]
	v_pk_mul_f32 v[116:117], v[112:113], s[100:101]
	v_exp_f32_e32 v114, v114
	v_exp_f32_e32 v115, v115
	v_exp_f32_e32 v116, v116
	v_exp_f32_e32 v117, v117
	v_pk_add_f32 v[114:115], v[114:115], s[98:99]
	v_pk_add_f32 v[116:117], v[116:117], s[98:99]
	v_rcp_f32_e32 v114, v114
	v_rcp_f32_e32 v115, v115
	v_rcp_f32_e32 v116, v116
	v_rcp_f32_e32 v117, v117
	v_pk_mul_f32 v[110:111], v[110:111], v[114:115]
	v_pk_mul_f32 v[112:113], v[112:113], v[116:117]
	v_pk_mul_f32 v[114:115], v[106:107], s[100:101]
	v_pk_mul_f32 v[116:117], v[108:109], s[100:101]
	v_exp_f32_e32 v114, v114
	v_exp_f32_e32 v115, v115
	v_exp_f32_e32 v116, v116
	v_exp_f32_e32 v117, v117
	v_pk_add_f32 v[114:115], v[114:115], s[98:99]
	v_pk_add_f32 v[116:117], v[116:117], s[98:99]
	v_rcp_f32_e32 v114, v114
	v_rcp_f32_e32 v115, v115
	v_rcp_f32_e32 v116, v116
	v_rcp_f32_e32 v117, v117
	v_pk_mul_f32 v[106:107], v[106:107], v[114:115]
	v_pk_mul_f32 v[108:109], v[108:109], v[116:117]
.LBB0_288:
	v_or_b32_e32 v114, 16, v168
	v_ashrrev_i32_e32 v115, 31, v114
	v_lshlrev_b64 v[114:115], 11, v[114:115]
	v_lshl_add_u64 v[114:115], v[130:131], 0, v[114:115]
	v_cvt_pk_bf16_f32 v110, v110, v111
	v_cvt_pk_bf16_f32 v111, v112, v113
	v_cvt_pk_bf16_f32 v112, v106, v107
	v_cvt_pk_bf16_f32 v113, v108, v109
	s_and_b64 vcc, exec, s[6:7]
	global_store_dwordx4 v[114:115], v[110:113], off
	s_cbranch_vccnz .LBB0_290
	v_pk_mul_f32 v[106:107], v[102:103], s[100:101]
	v_pk_mul_f32 v[108:109], v[104:105], s[100:101]
	v_exp_f32_e32 v106, v106
	v_exp_f32_e32 v107, v107
	v_exp_f32_e32 v108, v108
	v_exp_f32_e32 v109, v109
	v_pk_add_f32 v[106:107], v[106:107], s[98:99]
	v_pk_add_f32 v[108:109], v[108:109], s[98:99]
	v_rcp_f32_e32 v106, v106
	v_rcp_f32_e32 v107, v107
	v_rcp_f32_e32 v108, v108
	v_rcp_f32_e32 v109, v109
	v_pk_mul_f32 v[102:103], v[102:103], v[106:107]
	v_pk_mul_f32 v[104:105], v[104:105], v[108:109]
	v_pk_mul_f32 v[106:107], v[98:99], s[100:101]
	v_pk_mul_f32 v[108:109], v[100:101], s[100:101]
	v_exp_f32_e32 v106, v106
	v_exp_f32_e32 v107, v107
	v_exp_f32_e32 v108, v108
	v_exp_f32_e32 v109, v109
	v_pk_add_f32 v[106:107], v[106:107], s[98:99]
	v_pk_add_f32 v[108:109], v[108:109], s[98:99]
	v_rcp_f32_e32 v106, v106
	v_rcp_f32_e32 v107, v107
	v_rcp_f32_e32 v108, v108
	v_rcp_f32_e32 v109, v109
	v_pk_mul_f32 v[98:99], v[98:99], v[106:107]
	v_pk_mul_f32 v[100:101], v[100:101], v[108:109]
; __device__ __forceinline__ u32x4 pack8(const f32x4 a, const f32x4 b) { u32x4 w; w.x = cvt_pk_bf16(a[0], a[1]); w.y = cvt_pk_bf16(a[2], a[3]); w.z = cvt_pk_bf16(b[0], b[1]); w.w = cvt_pk_bf16(b[2], b[3]); return w; }
; #define EPI_ROWLOOP _Pragma("unroll") for (int ai = 0; ai < 2; ++ai) _Pragma("unroll") for (int m = 0; m < 4; ++m)
; __device__ __forceinline__ float sigm(float x) { return __builtin_amdgcn_rcpf(1.0f + __builtin_amdgcn_exp2f(x * -1.4426950408889634f)); }
; __device__ __forceinline__ float sigm_new(float x) { return __builtin_amdgcn_rcpf(1.0f + __builtin_amdgcn_exp2f(x * -1.4426950408889634f)); }
; __device__ __forceinline__ f32x4 sigm4_new(const f32x4 v) { f32x4 o; o[0] = sigm_new(v[0]); o[1] = sigm_new(v[1]); o[2] = sigm_new(v[2]); o[3] = sigm_new(v[3]); return o; }
; __device__ __forceinline__ f32x4 silu4_new(const f32x4 v) { return v * sigm4_new(v); }
; __device__ __forceinline__ f32x4 sigm4(const f32x4 v) { f32x4 o; o[0] = sigm(v[0]); o[1] = sigm(v[1]); o[2] = sigm(v[2]); o[3] = sigm(v[3]); return o; }
; __device__ __forceinline__ f32x4 silu4(const f32x4 v) { return v * sigm4(v); }
;     __device__ __forceinline__ void operator()(const f32x4 (&acc)[2][2][4][2], const Unit& u, int wr, int wc, int fr, int fq) const {
;     ...
;             bf16_t* base = pn < 4 ? HQ : pn < 8 ? HF : pn < 12 ? HI : HG; const bool act = (pn < 4) || (pn >= 12);
;             const int col0 = (pn & 3) * 256 + cl;
;             EPI_ROWLOOP { bf16_t* rowp = base + (size_t)(row0 + ai * HALF + m * 16) * 1024 + col0;
; #pragma unroll
;                 for (int bj = 0; bj < 2; ++bj) { f32x4 v0 = acc[ai][bj][m][0], v1 = acc[ai][bj][m][1]; if (act) { v0 = silu4(v0); v1 = silu4(v1); }
;                     *(u32x4*)(rowp + bj * HALF) = pack8(v0, v1); } }
.LBB0_290:
	v_cvt_pk_bf16_f32 v102, v102, v103
	v_cvt_pk_bf16_f32 v103, v104, v105
	v_cvt_pk_bf16_f32 v104, v98, v99
	v_cvt_pk_bf16_f32 v105, v100, v101
	s_and_b64 vcc, exec, s[6:7]
	global_store_dwordx4 v[114:115], v[102:105], off offset:256
	s_cbranch_vccnz .LBB0_292
	v_pk_mul_f32 v[98:99], v[94:95], s[100:101]
	v_pk_mul_f32 v[100:101], v[96:97], s[100:101]
	v_exp_f32_e32 v98, v98
	v_exp_f32_e32 v99, v99
	v_exp_f32_e32 v100, v100
	v_exp_f32_e32 v101, v101
	v_pk_add_f32 v[98:99], v[98:99], s[98:99]
	v_pk_add_f32 v[100:101], v[100:101], s[98:99]
	v_rcp_f32_e32 v98, v98
	v_rcp_f32_e32 v99, v99
	v_rcp_f32_e32 v100, v100
	v_rcp_f32_e32 v101, v101
	v_pk_mul_f32 v[94:95], v[94:95], v[98:99]
	v_pk_mul_f32 v[96:97], v[96:97], v[100:101]
	v_pk_mul_f32 v[98:99], v[90:91], s[100:101]
	v_pk_mul_f32 v[100:101], v[92:93], s[100:101]
	v_exp_f32_e32 v98, v98
	v_exp_f32_e32 v99, v99
	v_exp_f32_e32 v100, v100
	v_exp_f32_e32 v101, v101
	v_pk_add_f32 v[98:99], v[98:99], s[98:99]
	v_pk_add_f32 v[100:101], v[100:101], s[98:99]
	v_rcp_f32_e32 v98, v98
	v_rcp_f32_e32 v99, v99
	v_rcp_f32_e32 v100, v100
	v_rcp_f32_e32 v101, v101
	v_pk_mul_f32 v[90:91], v[90:91], v[98:99]
	v_pk_mul_f32 v[92:93], v[92:93], v[100:101]
.LBB0_292:
	v_or_b32_e32 v98, 32, v168
	v_ashrrev_i32_e32 v99, 31, v98
	v_lshlrev_b64 v[98:99], 11, v[98:99]
	v_lshl_add_u64 v[98:99], v[130:131], 0, v[98:99]
	v_cvt_pk_bf16_f32 v94, v94, v95
	v_cvt_pk_bf16_f32 v95, v96, v97
	v_cvt_pk_bf16_f32 v96, v90, v91
	v_cvt_pk_bf16_f32 v97, v92, v93
	s_and_b64 vcc, exec, s[6:7]
	global_store_dwordx4 v[98:99], v[94:97], off
	s_cbranch_vccnz .LBB0_294
	v_pk_mul_f32 v[90:91], v[86:87], s[100:101]
	v_pk_mul_f32 v[92:93], v[88:89], s[100:101]
	v_exp_f32_e32 v90, v90
	v_exp_f32_e32 v91, v91
	v_exp_f32_e32 v92, v92
	v_exp_f32_e32 v93, v93
	v_pk_add_f32 v[90:91], v[90:91], s[98:99]
	v_pk_add_f32 v[92:93], v[92:93], s[98:99]
	v_rcp_f32_e32 v90, v90
	v_rcp_f32_e32 v91, v91
	v_rcp_f32_e32 v92, v92
	v_rcp_f32_e32 v93, v93
	v_pk_mul_f32 v[86:87], v[86:87], v[90:91]
	v_pk_mul_f32 v[88:89], v[88:89], v[92:93]
	v_pk_mul_f32 v[90:91], v[82:83], s[100:101]
	v_pk_mul_f32 v[92:93], v[84:85], s[100:101]
	v_exp_f32_e32 v90, v90
	v_exp_f32_e32 v91, v91
	v_exp_f32_e32 v92, v92
	v_exp_f32_e32 v93, v93
	v_pk_add_f32 v[90:91], v[90:91], s[98:99]
	v_pk_add_f32 v[92:93], v[92:93], s[98:99]
	v_rcp_f32_e32 v90, v90
	v_rcp_f32_e32 v91, v91
	v_rcp_f32_e32 v92, v92
	v_rcp_f32_e32 v93, v93
	v_pk_mul_f32 v[82:83], v[82:83], v[90:91]
	v_pk_mul_f32 v[84:85], v[84:85], v[92:93]
.LBB0_294:
	v_cvt_pk_bf16_f32 v86, v86, v87
	v_cvt_pk_bf16_f32 v87, v88, v89
	v_cvt_pk_bf16_f32 v88, v82, v83
	v_cvt_pk_bf16_f32 v89, v84, v85
	s_and_b64 vcc, exec, s[6:7]
	global_store_dwordx4 v[98:99], v[86:89], off offset:256
	s_cbranch_vccnz .LBB0_296
	v_pk_mul_f32 v[82:83], v[78:79], s[100:101]
	v_pk_mul_f32 v[84:85], v[80:81], s[100:101]
	v_exp_f32_e32 v82, v82
	v_exp_f32_e32 v83, v83
	v_exp_f32_e32 v84, v84
	v_exp_f32_e32 v85, v85
	v_pk_add_f32 v[82:83], v[82:83], s[98:99]
	v_pk_add_f32 v[84:85], v[84:85], s[98:99]
	v_rcp_f32_e32 v82, v82
	v_rcp_f32_e32 v83, v83
	v_rcp_f32_e32 v84, v84
	v_rcp_f32_e32 v85, v85
	v_pk_mul_f32 v[78:79], v[78:79], v[82:83]
	v_pk_mul_f32 v[80:81], v[80:81], v[84:85]
	v_pk_mul_f32 v[82:83], v[74:75], s[100:101]
	v_pk_mul_f32 v[84:85], v[76:77], s[100:101]
	v_exp_f32_e32 v82, v82
	v_exp_f32_e32 v83, v83
	v_exp_f32_e32 v84, v84
	v_exp_f32_e32 v85, v85
	v_pk_add_f32 v[82:83], v[82:83], s[98:99]
	v_pk_add_f32 v[84:85], v[84:85], s[98:99]
	v_rcp_f32_e32 v82, v82
	v_rcp_f32_e32 v83, v83
	v_rcp_f32_e32 v84, v84
	v_rcp_f32_e32 v85, v85
	v_pk_mul_f32 v[74:75], v[74:75], v[82:83]
	v_pk_mul_f32 v[76:77], v[76:77], v[84:85]
.LBB0_296:
	v_or_b32_e32 v82, 48, v168
	v_ashrrev_i32_e32 v83, 31, v82
	v_lshlrev_b64 v[82:83], 11, v[82:83]
	v_lshl_add_u64 v[82:83], v[130:131], 0, v[82:83]
	v_cvt_pk_bf16_f32 v78, v78, v79
	v_cvt_pk_bf16_f32 v79, v80, v81
	v_cvt_pk_bf16_f32 v80, v74, v75
	v_cvt_pk_bf16_f32 v81, v76, v77
	s_and_b64 vcc, exec, s[6:7]
	global_store_dwordx4 v[82:83], v[78:81], off
	s_cbranch_vccnz .LBB0_298
	v_pk_mul_f32 v[74:75], v[70:71], s[100:101]
	v_pk_mul_f32 v[76:77], v[72:73], s[100:101]
	v_exp_f32_e32 v74, v74
	v_exp_f32_e32 v75, v75
	v_exp_f32_e32 v76, v76
	v_exp_f32_e32 v77, v77
	v_pk_add_f32 v[74:75], v[74:75], s[98:99]
	v_pk_add_f32 v[76:77], v[76:77], s[98:99]
	v_rcp_f32_e32 v74, v74
	v_rcp_f32_e32 v75, v75
	v_rcp_f32_e32 v76, v76
	v_rcp_f32_e32 v77, v77
	v_pk_mul_f32 v[70:71], v[70:71], v[74:75]
	v_pk_mul_f32 v[72:73], v[72:73], v[76:77]
	v_pk_mul_f32 v[74:75], v[66:67], s[100:101]
	v_pk_mul_f32 v[76:77], v[68:69], s[100:101]
	v_exp_f32_e32 v74, v74
	v_exp_f32_e32 v75, v75
	v_exp_f32_e32 v76, v76
	v_exp_f32_e32 v77, v77
	v_pk_add_f32 v[74:75], v[74:75], s[98:99]
	v_pk_add_f32 v[76:77], v[76:77], s[98:99]
	v_rcp_f32_e32 v74, v74
	v_rcp_f32_e32 v75, v75
	v_rcp_f32_e32 v76, v76
	v_rcp_f32_e32 v77, v77
	v_pk_mul_f32 v[66:67], v[66:67], v[74:75]
	v_pk_mul_f32 v[68:69], v[68:69], v[76:77]
.LBB0_298:
	v_cvt_pk_bf16_f32 v70, v70, v71
	v_cvt_pk_bf16_f32 v71, v72, v73
	v_cvt_pk_bf16_f32 v72, v66, v67
	v_cvt_pk_bf16_f32 v73, v68, v69
	s_and_b64 vcc, exec, s[6:7]
	global_store_dwordx4 v[82:83], v[70:73], off offset:256
	s_cbranch_vccnz .LBB0_300
	v_pk_mul_f32 v[66:67], v[62:63], s[100:101]
	v_pk_mul_f32 v[68:69], v[64:65], s[100:101]
	v_exp_f32_e32 v66, v66
	v_exp_f32_e32 v67, v67
	v_exp_f32_e32 v68, v68
	v_exp_f32_e32 v69, v69
	v_pk_add_f32 v[66:67], v[66:67], s[98:99]
	v_pk_add_f32 v[68:69], v[68:69], s[98:99]
	v_rcp_f32_e32 v66, v66
	v_rcp_f32_e32 v67, v67
	v_rcp_f32_e32 v68, v68
	v_rcp_f32_e32 v69, v69
	v_pk_mul_f32 v[62:63], v[62:63], v[66:67]
	v_pk_mul_f32 v[64:65], v[64:65], v[68:69]
	v_pk_mul_f32 v[66:67], v[58:59], s[100:101]
	v_pk_mul_f32 v[68:69], v[60:61], s[100:101]
	v_exp_f32_e32 v66, v66
	v_exp_f32_e32 v67, v67
	v_exp_f32_e32 v68, v68
	v_exp_f32_e32 v69, v69
	v_pk_add_f32 v[66:67], v[66:67], s[98:99]
	v_pk_add_f32 v[68:69], v[68:69], s[98:99]
	v_rcp_f32_e32 v66, v66
	v_rcp_f32_e32 v67, v67
	v_rcp_f32_e32 v68, v68
	v_rcp_f32_e32 v69, v69
	v_pk_mul_f32 v[58:59], v[58:59], v[66:67]
	v_pk_mul_f32 v[60:61], v[60:61], v[68:69]
; __device__ __forceinline__ u32x4 pack8(const f32x4 a, const f32x4 b) { u32x4 w; w.x = cvt_pk_bf16(a[0], a[1]); w.y = cvt_pk_bf16(a[2], a[3]); w.z = cvt_pk_bf16(b[0], b[1]); w.w = cvt_pk_bf16(b[2], b[3]); return w; }
; #define EPI_ROWLOOP _Pragma("unroll") for (int ai = 0; ai < 2; ++ai) _Pragma("unroll") for (int m = 0; m < 4; ++m)
; __device__ __forceinline__ float sigm(float x) { return __builtin_amdgcn_rcpf(1.0f + __builtin_amdgcn_exp2f(x * -1.4426950408889634f)); }
; __device__ __forceinline__ float sigm_new(float x) { return __builtin_amdgcn_rcpf(1.0f + __builtin_amdgcn_exp2f(x * -1.4426950408889634f)); }
; __device__ __forceinline__ f32x4 sigm4_new(const f32x4 v) { f32x4 o; o[0] = sigm_new(v[0]); o[1] = sigm_new(v[1]); o[2] = sigm_new(v[2]); o[3] = sigm_new(v[3]); return o; }
; __device__ __forceinline__ f32x4 silu4_new(const f32x4 v) { return v * sigm4_new(v); }
; __device__ __forceinline__ f32x4 sigm4(const f32x4 v) { f32x4 o; o[0] = sigm(v[0]); o[1] = sigm(v[1]); o[2] = sigm(v[2]); o[3] = sigm(v[3]); return o; }
; __device__ __forceinline__ f32x4 silu4(const f32x4 v) { return v * sigm4(v); }
;     __device__ __forceinline__ void operator()(const f32x4 (&acc)[2][2][4][2], const Unit& u, int wr, int wc, int fr, int fq) const {
;     ...
;             bf16_t* base = pn < 4 ? HQ : pn < 8 ? HF : pn < 12 ? HI : HG; const bool act = (pn < 4) || (pn >= 12);
;             const int col0 = (pn & 3) * 256 + cl;
;             EPI_ROWLOOP { bf16_t* rowp = base + (size_t)(row0 + ai * HALF + m * 16) * 1024 + col0;
; #pragma unroll
;                 for (int bj = 0; bj < 2; ++bj) { f32x4 v0 = acc[ai][bj][m][0], v1 = acc[ai][bj][m][1]; if (act) { v0 = silu4(v0); v1 = silu4(v1); }
;                     *(u32x4*)(rowp + bj * HALF) = pack8(v0, v1); } }
.LBB0_300:
	v_lshlrev_b64 v[66:67], 11, v[168:169]
	v_lshl_add_u64 v[66:67], v[130:131], 0, v[66:67]
	v_cvt_pk_bf16_f32 v62, v62, v63
	v_cvt_pk_bf16_f32 v63, v64, v65
	v_cvt_pk_bf16_f32 v64, v58, v59
	v_add_co_u32_e32 v58, vcc, 0x40000, v66
	v_cvt_pk_bf16_f32 v65, v60, v61
	s_nop 0
	v_addc_co_u32_e32 v59, vcc, 0, v67, vcc
	s_and_b64 vcc, exec, s[6:7]
	global_store_dwordx4 v[58:59], v[62:65], off
	s_cbranch_vccnz .LBB0_302
	v_pk_mul_f32 v[58:59], v[54:55], s[100:101]
	v_pk_mul_f32 v[60:61], v[56:57], s[100:101]
	v_exp_f32_e32 v58, v58
	v_exp_f32_e32 v59, v59
	v_exp_f32_e32 v60, v60
	v_exp_f32_e32 v61, v61
	v_pk_add_f32 v[58:59], v[58:59], s[98:99]
	v_pk_add_f32 v[60:61], v[60:61], s[98:99]
	v_rcp_f32_e32 v58, v58
	v_rcp_f32_e32 v59, v59
	v_rcp_f32_e32 v60, v60
	v_rcp_f32_e32 v61, v61
	v_pk_mul_f32 v[54:55], v[54:55], v[58:59]
	v_pk_mul_f32 v[56:57], v[56:57], v[60:61]
	v_pk_mul_f32 v[58:59], v[50:51], s[100:101]
	v_pk_mul_f32 v[60:61], v[52:53], s[100:101]
	v_exp_f32_e32 v58, v58
	v_exp_f32_e32 v59, v59
	v_exp_f32_e32 v60, v60
	v_exp_f32_e32 v61, v61
	v_pk_add_f32 v[58:59], v[58:59], s[98:99]
	v_pk_add_f32 v[60:61], v[60:61], s[98:99]
	v_rcp_f32_e32 v58, v58
	v_rcp_f32_e32 v59, v59
	v_rcp_f32_e32 v60, v60
	v_rcp_f32_e32 v61, v61
	v_pk_mul_f32 v[50:51], v[50:51], v[58:59]
	v_pk_mul_f32 v[52:53], v[52:53], v[60:61]
.LBB0_302:
	s_mov_b64 s[0:1], 0x40000
	v_lshl_add_u64 v[58:59], v[66:67], 0, s[0:1]
	v_cvt_pk_bf16_f32 v54, v54, v55
	v_cvt_pk_bf16_f32 v55, v56, v57
	v_cvt_pk_bf16_f32 v56, v50, v51
	v_cvt_pk_bf16_f32 v57, v52, v53
	s_and_b64 vcc, exec, s[6:7]
	global_store_dwordx4 v[58:59], v[54:57], off offset:256
	s_cbranch_vccnz .LBB0_304
	v_pk_mul_f32 v[50:51], v[46:47], s[100:101]
	v_pk_mul_f32 v[52:53], v[48:49], s[100:101]
	v_exp_f32_e32 v50, v50
	v_exp_f32_e32 v51, v51
	v_exp_f32_e32 v52, v52
	v_exp_f32_e32 v53, v53
	v_pk_add_f32 v[50:51], v[50:51], s[98:99]
	v_pk_add_f32 v[52:53], v[52:53], s[98:99]
	v_rcp_f32_e32 v50, v50
	v_rcp_f32_e32 v51, v51
	v_rcp_f32_e32 v52, v52
	v_rcp_f32_e32 v53, v53
	v_pk_mul_f32 v[46:47], v[46:47], v[50:51]
	v_pk_mul_f32 v[48:49], v[48:49], v[52:53]
	v_pk_mul_f32 v[50:51], v[42:43], s[100:101]
	v_pk_mul_f32 v[52:53], v[44:45], s[100:101]
	v_exp_f32_e32 v50, v50
	v_exp_f32_e32 v51, v51
	v_exp_f32_e32 v52, v52
	v_exp_f32_e32 v53, v53
	v_pk_add_f32 v[50:51], v[50:51], s[98:99]
	v_pk_add_f32 v[52:53], v[52:53], s[98:99]
	v_rcp_f32_e32 v50, v50
	v_rcp_f32_e32 v51, v51
	v_rcp_f32_e32 v52, v52
	v_rcp_f32_e32 v53, v53
	v_pk_mul_f32 v[42:43], v[42:43], v[50:51]
	v_pk_mul_f32 v[44:45], v[44:45], v[52:53]
.LBB0_304:
	v_lshlrev_b64 v[50:51], 11, v[168:169]
	v_lshl_add_u64 v[50:51], v[130:131], 0, v[50:51]
	v_cvt_pk_bf16_f32 v46, v46, v47
	v_cvt_pk_bf16_f32 v47, v48, v49
	v_cvt_pk_bf16_f32 v48, v42, v43
	v_add_co_u32_e32 v42, vcc, 0x48000, v50
	v_cvt_pk_bf16_f32 v49, v44, v45
	s_nop 0
	v_addc_co_u32_e32 v43, vcc, 0, v51, vcc
	s_and_b64 vcc, exec, s[6:7]
	global_store_dwordx4 v[42:43], v[46:49], off
	s_cbranch_vccnz .LBB0_306
	v_pk_mul_f32 v[42:43], v[38:39], s[100:101]
	v_pk_mul_f32 v[44:45], v[40:41], s[100:101]
	v_exp_f32_e32 v42, v42
	v_exp_f32_e32 v43, v43
	v_exp_f32_e32 v44, v44
	v_exp_f32_e32 v45, v45
	v_pk_add_f32 v[42:43], v[42:43], s[98:99]
	v_pk_add_f32 v[44:45], v[44:45], s[98:99]
	v_rcp_f32_e32 v42, v42
	v_rcp_f32_e32 v43, v43
	v_rcp_f32_e32 v44, v44
	v_rcp_f32_e32 v45, v45
	v_pk_mul_f32 v[38:39], v[38:39], v[42:43]
	v_pk_mul_f32 v[40:41], v[40:41], v[44:45]
	v_pk_mul_f32 v[42:43], v[34:35], s[100:101]
	v_pk_mul_f32 v[44:45], v[36:37], s[100:101]
	v_exp_f32_e32 v42, v42
	v_exp_f32_e32 v43, v43
	v_exp_f32_e32 v44, v44
	v_exp_f32_e32 v45, v45
	v_pk_add_f32 v[42:43], v[42:43], s[98:99]
	v_pk_add_f32 v[44:45], v[44:45], s[98:99]
	v_rcp_f32_e32 v42, v42
	v_rcp_f32_e32 v43, v43
	v_rcp_f32_e32 v44, v44
	v_rcp_f32_e32 v45, v45
	v_pk_mul_f32 v[34:35], v[34:35], v[42:43]
	v_pk_mul_f32 v[36:37], v[36:37], v[44:45]
; __device__ __forceinline__ u32x4 pack8(const f32x4 a, const f32x4 b) { u32x4 w; w.x = cvt_pk_bf16(a[0], a[1]); w.y = cvt_pk_bf16(a[2], a[3]); w.z = cvt_pk_bf16(b[0], b[1]); w.w = cvt_pk_bf16(b[2], b[3]); return w; }
; #define EPI_ROWLOOP _Pragma("unroll") for (int ai = 0; ai < 2; ++ai) _Pragma("unroll") for (int m = 0; m < 4; ++m)
; __device__ __forceinline__ float sigm(float x) { return __builtin_amdgcn_rcpf(1.0f + __builtin_amdgcn_exp2f(x * -1.4426950408889634f)); }
; __device__ __forceinline__ float sigm_new(float x) { return __builtin_amdgcn_rcpf(1.0f + __builtin_amdgcn_exp2f(x * -1.4426950408889634f)); }
; __device__ __forceinline__ f32x4 sigm4_new(const f32x4 v) { f32x4 o; o[0] = sigm_new(v[0]); o[1] = sigm_new(v[1]); o[2] = sigm_new(v[2]); o[3] = sigm_new(v[3]); return o; }
; __device__ __forceinline__ f32x4 silu4_new(const f32x4 v) { return v * sigm4_new(v); }
; __device__ __forceinline__ f32x4 sigm4(const f32x4 v) { f32x4 o; o[0] = sigm(v[0]); o[1] = sigm(v[1]); o[2] = sigm(v[2]); o[3] = sigm(v[3]); return o; }
; __device__ __forceinline__ f32x4 silu4(const f32x4 v) { return v * sigm4(v); }
;     __device__ __forceinline__ void operator()(const f32x4 (&acc)[2][2][4][2], const Unit& u, int wr, int wc, int fr, int fq) const {
;     ...
;             bf16_t* base = pn < 4 ? HQ : pn < 8 ? HF : pn < 12 ? HI : HG; const bool act = (pn < 4) || (pn >= 12);
;             const int col0 = (pn & 3) * 256 + cl;
;             EPI_ROWLOOP { bf16_t* rowp = base + (size_t)(row0 + ai * HALF + m * 16) * 1024 + col0;
; #pragma unroll
;                 for (int bj = 0; bj < 2; ++bj) { f32x4 v0 = acc[ai][bj][m][0], v1 = acc[ai][bj][m][1]; if (act) { v0 = silu4(v0); v1 = silu4(v1); }
;                     *(u32x4*)(rowp + bj * HALF) = pack8(v0, v1); } }
.LBB0_306:
	s_mov_b64 s[0:1], 0x48000
	v_lshl_add_u64 v[42:43], v[50:51], 0, s[0:1]
	v_cvt_pk_bf16_f32 v38, v38, v39
	v_cvt_pk_bf16_f32 v39, v40, v41
	v_cvt_pk_bf16_f32 v40, v34, v35
	v_cvt_pk_bf16_f32 v41, v36, v37
	s_and_b64 vcc, exec, s[6:7]
	global_store_dwordx4 v[42:43], v[38:41], off offset:256
	s_cbranch_vccnz .LBB0_308
	v_pk_mul_f32 v[34:35], v[30:31], s[100:101]
	v_pk_mul_f32 v[36:37], v[32:33], s[100:101]
	v_exp_f32_e32 v34, v34
	v_exp_f32_e32 v35, v35
	v_exp_f32_e32 v36, v36
	v_exp_f32_e32 v37, v37
	v_pk_add_f32 v[34:35], v[34:35], s[98:99]
	v_pk_add_f32 v[36:37], v[36:37], s[98:99]
	v_rcp_f32_e32 v34, v34
	v_rcp_f32_e32 v35, v35
	v_rcp_f32_e32 v36, v36
	v_rcp_f32_e32 v37, v37
	v_pk_mul_f32 v[30:31], v[30:31], v[34:35]
	v_pk_mul_f32 v[32:33], v[32:33], v[36:37]
	v_pk_mul_f32 v[34:35], v[26:27], s[100:101]
	v_pk_mul_f32 v[36:37], v[28:29], s[100:101]
	v_exp_f32_e32 v34, v34
	v_exp_f32_e32 v35, v35
	v_exp_f32_e32 v36, v36
	v_exp_f32_e32 v37, v37
	v_pk_add_f32 v[34:35], v[34:35], s[98:99]
	v_pk_add_f32 v[36:37], v[36:37], s[98:99]
	v_rcp_f32_e32 v34, v34
	v_rcp_f32_e32 v35, v35
	v_rcp_f32_e32 v36, v36
	v_rcp_f32_e32 v37, v37
	v_pk_mul_f32 v[26:27], v[26:27], v[34:35]
	v_pk_mul_f32 v[28:29], v[28:29], v[36:37]
.LBB0_308:
	v_lshlrev_b64 v[34:35], 11, v[168:169]
	v_lshl_add_u64 v[34:35], v[130:131], 0, v[34:35]
	v_cvt_pk_bf16_f32 v30, v30, v31
	v_cvt_pk_bf16_f32 v31, v32, v33
	v_cvt_pk_bf16_f32 v32, v26, v27
	v_add_co_u32_e32 v26, vcc, 0x50000, v34
	v_cvt_pk_bf16_f32 v33, v28, v29
	s_nop 0
	v_addc_co_u32_e32 v27, vcc, 0, v35, vcc
	s_and_b64 vcc, exec, s[6:7]
	global_store_dwordx4 v[26:27], v[30:33], off
	s_cbranch_vccnz .LBB0_310
	v_pk_mul_f32 v[26:27], v[22:23], s[100:101]
	v_pk_mul_f32 v[28:29], v[24:25], s[100:101]
	v_exp_f32_e32 v26, v26
	v_exp_f32_e32 v27, v27
	v_exp_f32_e32 v28, v28
	v_exp_f32_e32 v29, v29
	v_pk_add_f32 v[26:27], v[26:27], s[98:99]
	v_pk_add_f32 v[28:29], v[28:29], s[98:99]
	v_rcp_f32_e32 v26, v26
	v_rcp_f32_e32 v27, v27
	v_rcp_f32_e32 v28, v28
	v_rcp_f32_e32 v29, v29
	v_pk_mul_f32 v[22:23], v[22:23], v[26:27]
	v_pk_mul_f32 v[24:25], v[24:25], v[28:29]
	v_pk_mul_f32 v[26:27], v[18:19], s[100:101]
	v_pk_mul_f32 v[28:29], v[20:21], s[100:101]
	v_exp_f32_e32 v26, v26
	v_exp_f32_e32 v27, v27
	v_exp_f32_e32 v28, v28
	v_exp_f32_e32 v29, v29
	v_pk_add_f32 v[26:27], v[26:27], s[98:99]
	v_pk_add_f32 v[28:29], v[28:29], s[98:99]
	v_rcp_f32_e32 v26, v26
	v_rcp_f32_e32 v27, v27
	v_rcp_f32_e32 v28, v28
	v_rcp_f32_e32 v29, v29
	v_pk_mul_f32 v[18:19], v[18:19], v[26:27]
	v_pk_mul_f32 v[20:21], v[20:21], v[28:29]
.LBB0_310:
	s_mov_b64 s[0:1], 0x50000
	v_lshl_add_u64 v[26:27], v[34:35], 0, s[0:1]
	v_cvt_pk_bf16_f32 v22, v22, v23
	v_cvt_pk_bf16_f32 v23, v24, v25
	v_cvt_pk_bf16_f32 v24, v18, v19
	v_cvt_pk_bf16_f32 v25, v20, v21
	s_and_b64 vcc, exec, s[6:7]
	global_store_dwordx4 v[26:27], v[22:25], off offset:256
	s_cbranch_vccnz .LBB0_312
	v_pk_mul_f32 v[18:19], v[14:15], s[100:101]
	v_pk_mul_f32 v[20:21], v[16:17], s[100:101]
	v_exp_f32_e32 v18, v18
	v_exp_f32_e32 v19, v19
	v_exp_f32_e32 v20, v20
	v_exp_f32_e32 v21, v21
	v_pk_add_f32 v[18:19], v[18:19], s[98:99]
	v_pk_add_f32 v[20:21], v[20:21], s[98:99]
	v_rcp_f32_e32 v18, v18
	v_rcp_f32_e32 v19, v19
	v_rcp_f32_e32 v20, v20
	v_rcp_f32_e32 v21, v21
	v_pk_mul_f32 v[14:15], v[14:15], v[18:19]
	v_pk_mul_f32 v[16:17], v[16:17], v[20:21]
	v_pk_mul_f32 v[18:19], v[10:11], s[100:101]
	v_pk_mul_f32 v[20:21], v[12:13], s[100:101]
	v_exp_f32_e32 v18, v18
	v_exp_f32_e32 v19, v19
	v_exp_f32_e32 v20, v20
	v_exp_f32_e32 v21, v21
	v_pk_add_f32 v[18:19], v[18:19], s[98:99]
	v_pk_add_f32 v[20:21], v[20:21], s[98:99]
	v_rcp_f32_e32 v18, v18
	v_rcp_f32_e32 v19, v19
	v_rcp_f32_e32 v20, v20
	v_rcp_f32_e32 v21, v21
	v_pk_mul_f32 v[10:11], v[10:11], v[18:19]
	v_pk_mul_f32 v[12:13], v[12:13], v[20:21]
